# diff attention x-query loops: 4th k-step QK chain accumulates directly into the score registers (K fragments in a dead VGPR quad), -m vector never clobbered so its save/restore/copy moves are gone; pl
# speedup vs baseline: 1.0258x; 1.0154x over previous
; #define MFMA(a, b, c) __builtin_amdgcn_mfma_f32_32x32x16_bf16((a), (b), (c), 0, 0, 0)
; DI int crow(int reg, int h) { return (reg & 3) + 8 * (reg >> 2) + 4 * h; }
; DI s16x4 vtr(const char* p) { return __builtin_bit_cast(s16x4, __builtin_amdgcn_ds_read_tr16_b64_v4i16((__attribute__((address_space(3))) v4i16_t*)(lds_cptr)p)); }
; template <int DV>
; DI void attn_core(const u16* __restrict__ P, size_t tokbase, int kcol, int vcol, int n1, int n2, int xs0,
;                   bool win, int tq, float m0, float l0, f32x16 (&o)[DV / 32], float& lsum, char* lds) {
;     ...
;       f32x16 pt = negm;
; #pragma unroll
;       for (int s = 0; s < 4; ++s) {
;         const int ch = 2 * s + h, key = 32 * ks + r;
;         const bf16x8 kf = *(const bf16x8*)(base + ch * 1024 + ((key ^ ch) * 16));
;         const bf16x8 qf = qreg[s];
;         pt = MFMA(kf, qf, pt);
;       }
;       if (domask) {
; #pragma unroll
;         for (int reg = 0; reg < 16; ++reg) {
;           const int d = tq - (kt0 + 32 * ks + crow(reg, h));
;           if (d > 128 || d < -128) pt[reg] = -1e30f;
;         }
;       }
;       float mloc = mx2(pt[0], pt[1]);
; #pragma unroll
;       for (int reg = 2; reg < 16; reg += 2) mloc = mx2(mx2(mloc, pt[reg]), pt[reg + 1]);
;       mloc = hmax(mloc);
;       const bool first = autoinit && it == 0 && ks == 0;
;       if (first || __builtin_amdgcn_ballot_w64(mloc > THR) != 0) {
;         const float d = first ? mloc : fmaxf(mloc, 0.f);
;         const float alpha = fexp2(-d);
;         m += d; l *= alpha;
; #pragma unroll
;         for (int reg = 0; reg < 16; ++reg) { negm[reg] = -m; pt[reg] -= d; }
; #pragma unroll
;         for (int b = 0; b < DV / 32; ++b)
; #pragma unroll
;           for (int reg = 0; reg < 16; ++reg) o[b][reg] *= alpha;
;       }
;       float la = 0.f;
; #pragma unroll
;       for (int reg = 0; reg < 16; ++reg) { const float e = fexp2(pt[reg]); pt[reg] = e; la += e; }
;       l += la;
; #pragma unroll
;       for (int s2 = 0; s2 < 2; ++s2) {
;         const bf16x8 pb = pack8(pt, s2);
;         const int s16 = 2 * ks + s2;
; #pragma unroll
;         for (int b = 0; b < DV / 32; ++b) {
;           const char* va = base + KB + b * 4096 + s16 * 1024 + trofs;
;           const bf16x8 vf = cat8(vtr(va), vtr(va + 512));
;           o[b] = MFMA(vf, pb, o[b]);
;         }
;       }
;     }
.LBB0_359:
.LBB0_360:
	v_exp_f32_e32 v96, v96
	v_exp_f32_e32 v97, v97
	v_exp_f32_e32 v98, v98
	v_exp_f32_e32 v99, v99
	v_add_f32_e32 v186, 0, v96
	v_exp_f32_e32 v100, v100
	v_add_f32_e32 v186, v97, v186
	v_exp_f32_e32 v101, v101
	v_add_f32_e32 v186, v98, v186
	v_exp_f32_e32 v102, v102
	v_add_f32_e32 v186, v99, v186
	v_exp_f32_e32 v103, v103
	v_add_f32_e32 v186, v100, v186
	v_add_f32_e32 v186, v101, v186
	v_add_f32_e32 v186, v102, v186
	v_add_f32_e32 v186, v103, v186
	v_cvt_pk_bf16_f32 v96, v96, v97
	v_cvt_pk_bf16_f32 v97, v98, v99
	v_cvt_pk_bf16_f32 v98, v100, v101
	v_cvt_pk_bf16_f32 v99, v102, v103
	ds_read_b64_tr_b16 v[100:101], v159 offset:8192
	ds_read_b64_tr_b16 v[102:103], v159 offset:8704
	s_waitcnt lgkmcnt(0)
	v_mfma_f32_32x32x16_bf16 v[48:63], v[100:103], v[96:99], v[48:63]
	ds_read_b64_tr_b16 v[100:101], v159 offset:12288
	ds_read_b64_tr_b16 v[102:103], v159 offset:12800
	v_exp_f32_e32 v104, v104
	v_exp_f32_e32 v105, v105
	v_exp_f32_e32 v106, v106
	v_exp_f32_e32 v107, v107
	v_exp_f32_e32 v108, v108
	v_exp_f32_e32 v109, v109
	s_waitcnt lgkmcnt(0)
	v_mfma_f32_32x32x16_bf16 v[32:47], v[100:103], v[96:99], v[32:47]
	ds_read_b64_tr_b16 v[100:101], v159 offset:16384
	ds_read_b64_tr_b16 v[102:103], v159 offset:16896
	v_exp_f32_e32 v110, v110
	v_exp_f32_e32 v111, v111
	v_add_f32_e32 v186, v104, v186
	v_add_f32_e32 v186, v105, v186
	v_add_f32_e32 v186, v106, v186
	v_add_f32_e32 v186, v107, v186
	s_waitcnt lgkmcnt(0)
	v_mfma_f32_32x32x16_bf16 v[16:31], v[100:103], v[96:99], v[16:31]
	ds_read_b64_tr_b16 v[100:101], v159 offset:20480
	ds_read_b64_tr_b16 v[102:103], v159 offset:20992
	v_add_f32_e32 v186, v108, v186
	v_add_f32_e32 v186, v109, v186
	v_add_f32_e32 v186, v110, v186
	v_add_f32_e32 v186, v111, v186
	v_add_f32_e32 v186, v185, v186
	s_waitcnt lgkmcnt(0)
	v_mfma_f32_32x32x16_bf16 v[0:15], v[100:103], v[96:99], v[0:15]
	ds_read_b64_tr_b16 v[100:101], v159 offset:9216
	ds_read_b64_tr_b16 v[102:103], v159 offset:9728
	v_cvt_pk_bf16_f32 v96, v104, v105
	v_cvt_pk_bf16_f32 v97, v106, v107
	v_cvt_pk_bf16_f32 v98, v108, v109
	v_cvt_pk_bf16_f32 v99, v110, v111
	s_waitcnt lgkmcnt(0)
	s_nop 0
	v_mfma_f32_32x32x16_bf16 v[48:63], v[100:103], v[96:99], v[48:63]
	ds_read_b64_tr_b16 v[100:101], v159 offset:13312
	ds_read_b64_tr_b16 v[102:103], v159 offset:13824
	s_waitcnt lgkmcnt(0)
	v_mfma_f32_32x32x16_bf16 v[32:47], v[100:103], v[96:99], v[32:47]
	ds_read_b64_tr_b16 v[100:101], v159 offset:17408
	ds_read_b64_tr_b16 v[102:103], v159 offset:17920
	s_waitcnt lgkmcnt(0)
	v_mfma_f32_32x32x16_bf16 v[16:31], v[100:103], v[96:99], v[16:31]
	ds_read_b64_tr_b16 v[100:101], v159 offset:21504
	ds_read_b64_tr_b16 v[102:103], v159 offset:22016
	ds_read_b128 v[206:209], v161
	s_waitcnt lgkmcnt(1)
	v_mfma_f32_32x32x16_bf16 v[0:15], v[100:103], v[96:99], v[0:15]
	s_waitcnt lgkmcnt(0)
	v_mfma_f32_32x32x16_bf16 v[96:111], v[206:209], v[112:115], v[80:95]
	ds_read_b128 v[206:209], v162
	s_waitcnt lgkmcnt(0)
	v_mfma_f32_32x32x16_bf16 v[96:111], v[206:209], v[116:119], v[96:111]
	ds_read_b128 v[206:209], v163
	s_waitcnt lgkmcnt(0)
	v_mfma_f32_32x32x16_bf16 v[96:111], v[206:209], v[120:123], v[96:111]
	ds_read_b128 v[206:209], v164
	s_waitcnt lgkmcnt(0)
	v_mfma_f32_32x32x16_bf16 v[96:111], v[206:209], v[124:127], v[96:111]
	s_nop 11
	v_maximum3_f32 v185, v96, v97, v97
	v_maximum3_f32 v185, v185, v98, v99
	v_maximum3_f32 v185, v185, v100, v101
	v_maximum3_f32 v185, v185, v102, v103
	v_maximum3_f32 v185, v185, v104, v105
	v_maximum3_f32 v185, v185, v106, v107
	v_maximum3_f32 v185, v185, v108, v109
	v_maximum3_f32 v185, v185, v110, v111
	v_mov_b32_e32 v187, v185
	s_nop 1
	v_permlane32_swap_b32_e32 v185, v187
	v_maximum3_f32 v185, v185, v187, v187
	v_cmp_lt_f32_e32 vcc, s80, v185
	s_cbranch_vccz .LBB0_362
; DI float fexp2(float x) { return __builtin_amdgcn_exp2f(x); }
; template <int DV>
; DI void attn_core(const u16* __restrict__ P, size_t tokbase, int kcol, int vcol, int n1, int n2, int xs0,
;                   bool win, int tq, float m0, float l0, f32x16 (&o)[DV / 32], float& lsum, char* lds) {
;     ...
;       if (first || __builtin_amdgcn_ballot_w64(mloc > THR) != 0) {
;         const float d = first ? mloc : fmaxf(mloc, 0.f);
;         const float alpha = fexp2(-d);
;         m += d; l *= alpha;
; #pragma unroll
;         for (int reg = 0; reg < 16; ++reg) { negm[reg] = -m; pt[reg] -= d; }
; #pragma unroll
;         for (int b = 0; b < DV / 32; ++b)
; #pragma unroll
;           for (int reg = 0; reg < 16; ++reg) o[b][reg] *= alpha;
;       }
	v_max_f32_e32 v64, v185, v185
	v_max_f32_e32 v64, 0, v64
	v_exp_f32_e64 v82, -v64
	v_add_f32_e32 v165, v165, v64
	v_xor_b32_e32 v80, 0x80000000, v165
	v_pk_add_f32 v[96:97], v[96:97], v[64:65] op_sel_hi:[1,0] neg_lo:[0,1] neg_hi:[0,1]
	v_mul_f32_e32 v186, v186, v82
	v_pk_add_f32 v[98:99], v[98:99], v[64:65] op_sel_hi:[1,0] neg_lo:[0,1] neg_hi:[0,1]
	v_pk_add_f32 v[100:101], v[100:101], v[64:65] op_sel_hi:[1,0] neg_lo:[0,1] neg_hi:[0,1]
	v_pk_add_f32 v[102:103], v[102:103], v[64:65] op_sel_hi:[1,0] neg_lo:[0,1] neg_hi:[0,1]
	v_pk_add_f32 v[104:105], v[104:105], v[64:65] op_sel_hi:[1,0] neg_lo:[0,1] neg_hi:[0,1]
	v_pk_add_f32 v[106:107], v[106:107], v[64:65] op_sel_hi:[1,0] neg_lo:[0,1] neg_hi:[0,1]
	v_pk_add_f32 v[108:109], v[108:109], v[64:65] op_sel_hi:[1,0] neg_lo:[0,1] neg_hi:[0,1]
	v_pk_add_f32 v[110:111], v[110:111], v[64:65] op_sel_hi:[1,0] neg_lo:[0,1] neg_hi:[0,1]
	v_pk_mul_f32 v[62:63], v[62:63], v[82:83] op_sel_hi:[1,0]
	v_pk_mul_f32 v[60:61], v[60:61], v[82:83] op_sel_hi:[1,0]
	v_pk_mul_f32 v[58:59], v[58:59], v[82:83] op_sel_hi:[1,0]
	v_pk_mul_f32 v[56:57], v[56:57], v[82:83] op_sel_hi:[1,0]
	v_pk_mul_f32 v[54:55], v[54:55], v[82:83] op_sel_hi:[1,0]
	v_pk_mul_f32 v[52:53], v[52:53], v[82:83] op_sel_hi:[1,0]
	v_pk_mul_f32 v[50:51], v[50:51], v[82:83] op_sel_hi:[1,0]
	v_pk_mul_f32 v[48:49], v[48:49], v[82:83] op_sel_hi:[1,0]
	v_pk_mul_f32 v[46:47], v[46:47], v[82:83] op_sel_hi:[1,0]
	v_pk_mul_f32 v[44:45], v[44:45], v[82:83] op_sel_hi:[1,0]
	v_pk_mul_f32 v[42:43], v[42:43], v[82:83] op_sel_hi:[1,0]
	v_pk_mul_f32 v[40:41], v[40:41], v[82:83] op_sel_hi:[1,0]
	v_pk_mul_f32 v[38:39], v[38:39], v[82:83] op_sel_hi:[1,0]
	v_pk_mul_f32 v[36:37], v[36:37], v[82:83] op_sel_hi:[1,0]
	v_pk_mul_f32 v[34:35], v[34:35], v[82:83] op_sel_hi:[1,0]
	v_pk_mul_f32 v[32:33], v[32:33], v[82:83] op_sel_hi:[1,0]
	v_pk_mul_f32 v[30:31], v[30:31], v[82:83] op_sel_hi:[1,0]
	v_pk_mul_f32 v[28:29], v[28:29], v[82:83] op_sel_hi:[1,0]
	v_pk_mul_f32 v[26:27], v[26:27], v[82:83] op_sel_hi:[1,0]
	v_pk_mul_f32 v[24:25], v[24:25], v[82:83] op_sel_hi:[1,0]
	v_pk_mul_f32 v[22:23], v[22:23], v[82:83] op_sel_hi:[1,0]
	v_pk_mul_f32 v[20:21], v[20:21], v[82:83] op_sel_hi:[1,0]
	v_pk_mul_f32 v[18:19], v[18:19], v[82:83] op_sel_hi:[1,0]
	v_pk_mul_f32 v[16:17], v[16:17], v[82:83] op_sel_hi:[1,0]
	v_pk_mul_f32 v[14:15], v[14:15], v[82:83] op_sel_hi:[1,0]
	v_pk_mul_f32 v[12:13], v[12:13], v[82:83] op_sel_hi:[1,0]
	v_pk_mul_f32 v[10:11], v[10:11], v[82:83] op_sel_hi:[1,0]
	v_pk_mul_f32 v[8:9], v[8:9], v[82:83] op_sel_hi:[1,0]
	v_pk_mul_f32 v[6:7], v[6:7], v[82:83] op_sel_hi:[1,0]
	v_pk_mul_f32 v[4:5], v[4:5], v[82:83] op_sel_hi:[1,0]
	v_pk_mul_f32 v[2:3], v[2:3], v[82:83] op_sel_hi:[1,0]
	v_pk_mul_f32 v[0:1], v[0:1], v[82:83] op_sel_hi:[1,0]
	v_mov_b32_e32 v81, v80
	v_mov_b32_e32 v82, v80
	v_mov_b32_e32 v83, v80
	v_mov_b32_e32 v84, v80
	v_mov_b32_e32 v85, v80
	v_mov_b32_e32 v86, v80
	v_mov_b32_e32 v87, v80
	v_mov_b32_e32 v88, v80
	v_mov_b32_e32 v89, v80
	v_mov_b32_e32 v90, v80
	v_mov_b32_e32 v91, v80
	v_mov_b32_e32 v92, v80
	v_mov_b32_e32 v93, v80
	v_mov_b32_e32 v94, v80
	v_mov_b32_e32 v95, v80
	v_mov_b32_e32 v64, v80
	v_mov_b32_e32 v166, v80
	v_mov_b32_e32 v168, v80
	v_mov_b32_e32 v169, v80
	v_mov_b32_e32 v170, v80
	v_mov_b32_e32 v171, v80
	v_mov_b32_e32 v172, v80
	v_mov_b32_e32 v174, v80
	v_mov_b32_e32 v175, v80
	v_mov_b32_e32 v176, v80
	v_mov_b32_e32 v177, v80
	v_mov_b32_e32 v178, v80
	v_mov_b32_e32 v179, v80
	v_mov_b32_e32 v180, v80
	v_mov_b32_e32 v182, v80
	v_mov_b32_e32 v183, v80

; #define MFMA(a, b, c) __builtin_amdgcn_mfma_f32_32x32x16_bf16((a), (b), (c), 0, 0, 0)
; DI int crow(int reg, int h) { return (reg & 3) + 8 * (reg >> 2) + 4 * h; }
; DI s16x4 vtr(const char* p) { return __builtin_bit_cast(s16x4, __builtin_amdgcn_ds_read_tr16_b64_v4i16((__attribute__((address_space(3))) v4i16_t*)(lds_cptr)p)); }
; template <int DV>
; DI void attn_core(const u16* __restrict__ P, size_t tokbase, int kcol, int vcol, int n1, int n2, int xs0,
;                   bool win, int tq, float m0, float l0, f32x16 (&o)[DV / 32], float& lsum, char* lds) {
;     ...
;       f32x16 pt = negm;
; #pragma unroll
;       for (int s = 0; s < 4; ++s) {
;         const int ch = 2 * s + h, key = 32 * ks + r;
;         const bf16x8 kf = *(const bf16x8*)(base + ch * 1024 + ((key ^ ch) * 16));
;         const bf16x8 qf = qreg[s];
;         pt = MFMA(kf, qf, pt);
;       }
;       if (domask) {
; #pragma unroll
;         for (int reg = 0; reg < 16; ++reg) {
;           const int d = tq - (kt0 + 32 * ks + crow(reg, h));
;           if (d > 128 || d < -128) pt[reg] = -1e30f;
;         }
;       }
;       float mloc = mx2(pt[0], pt[1]);
; #pragma unroll
;       for (int reg = 2; reg < 16; reg += 2) mloc = mx2(mx2(mloc, pt[reg]), pt[reg + 1]);
;       mloc = hmax(mloc);
;       const bool first = autoinit && it == 0 && ks == 0;
;       if (first || __builtin_amdgcn_ballot_w64(mloc > THR) != 0) {
;         const float d = first ? mloc : fmaxf(mloc, 0.f);
;         const float alpha = fexp2(-d);
;         m += d; l *= alpha;
; #pragma unroll
;         for (int reg = 0; reg < 16; ++reg) { negm[reg] = -m; pt[reg] -= d; }
; #pragma unroll
;         for (int b = 0; b < DV / 32; ++b)
; #pragma unroll
;           for (int reg = 0; reg < 16; ++reg) o[b][reg] *= alpha;
;       }
;       float la = 0.f;
; #pragma unroll
;       for (int reg = 0; reg < 16; ++reg) { const float e = fexp2(pt[reg]); pt[reg] = e; la += e; }
;       l += la;
; #pragma unroll
;       for (int s2 = 0; s2 < 2; ++s2) {
;         const bf16x8 pb = pack8(pt, s2);
;         const int s16 = 2 * ks + s2;
; #pragma unroll
;         for (int b = 0; b < DV / 32; ++b) {
;           const char* va = base + KB + b * 4096 + s16 * 1024 + trofs;
;           const bf16x8 vf = cat8(vtr(va), vtr(va + 512));
;           o[b] = MFMA(vf, pb, o[b]);
;         }
;       }
;     }
.LBB0_366:
	v_exp_f32_e32 v79, v96
	v_exp_f32_e32 v97, v97
	v_exp_f32_e32 v98, v98
	v_exp_f32_e32 v99, v99
	v_add_f32_e32 v96, 0, v79
	v_exp_f32_e32 v100, v100
	v_add_f32_e32 v96, v97, v96
	v_exp_f32_e32 v101, v101
	v_add_f32_e32 v96, v98, v96
	v_exp_f32_e32 v102, v102
	v_add_f32_e32 v96, v99, v96
	v_exp_f32_e32 v103, v103
	v_add_f32_e32 v96, v100, v96
	v_exp_f32_e32 v104, v104
	v_add_f32_e32 v96, v101, v96
	v_exp_f32_e32 v105, v105
	v_add_f32_e32 v96, v102, v96
	v_exp_f32_e32 v106, v106
	v_add_f32_e32 v96, v103, v96
	v_exp_f32_e32 v107, v107
	v_add_f32_e32 v96, v104, v96
	v_exp_f32_e32 v108, v108
	v_add_f32_e32 v96, v105, v96
	v_exp_f32_e32 v109, v109
	v_add_f32_e32 v96, v106, v96
	v_exp_f32_e32 v110, v110
	v_add_f32_e32 v96, v107, v96
	v_exp_f32_e32 v111, v111
	v_add_f32_e32 v96, v108, v96
	v_add_f32_e32 v96, v109, v96
	v_add_f32_e32 v96, v110, v96
	v_add_f32_e32 v96, v111, v96
	v_add_f32_e32 v78, v78, v96
	v_cvt_pk_bf16_f32 v96, v79, v97
	v_cvt_pk_bf16_f32 v97, v98, v99
	v_cvt_pk_bf16_f32 v98, v100, v101
	v_cvt_pk_bf16_f32 v99, v102, v103
	ds_read_b64_tr_b16 v[100:101], v159 offset:32768
	ds_read_b64_tr_b16 v[102:103], v159 offset:33280
	s_waitcnt lgkmcnt(0)
	v_mfma_f32_32x32x16_bf16 v[48:63], v[100:103], v[96:99], v[48:63]
	ds_read_b64_tr_b16 v[100:101], v159 offset:36864
	ds_read_b64_tr_b16 v[102:103], v159 offset:37376
	s_waitcnt lgkmcnt(0)
	v_mfma_f32_32x32x16_bf16 v[32:47], v[100:103], v[96:99], v[32:47]
	ds_read_b64_tr_b16 v[100:101], v159 offset:40960
	ds_read_b64_tr_b16 v[102:103], v159 offset:41472
	s_waitcnt lgkmcnt(0)
	v_mfma_f32_32x32x16_bf16 v[16:31], v[100:103], v[96:99], v[16:31]
	ds_read_b64_tr_b16 v[100:101], v159 offset:45056
	ds_read_b64_tr_b16 v[102:103], v159 offset:45568
	s_waitcnt lgkmcnt(0)
	v_mfma_f32_32x32x16_bf16 v[0:15], v[100:103], v[96:99], v[0:15]
	ds_read_b64_tr_b16 v[100:101], v159 offset:33792
	ds_read_b64_tr_b16 v[102:103], v159 offset:34304
	v_cvt_pk_bf16_f32 v96, v104, v105
	v_cvt_pk_bf16_f32 v97, v106, v107
	v_cvt_pk_bf16_f32 v98, v108, v109
	v_cvt_pk_bf16_f32 v99, v110, v111
	s_waitcnt lgkmcnt(0)
	s_nop 0
	v_mfma_f32_32x32x16_bf16 v[48:63], v[100:103], v[96:99], v[48:63]
	ds_read_b64_tr_b16 v[100:101], v159 offset:37888
	ds_read_b64_tr_b16 v[102:103], v159 offset:38400
	s_waitcnt lgkmcnt(0)
	v_mfma_f32_32x32x16_bf16 v[32:47], v[100:103], v[96:99], v[32:47]
	ds_read_b64_tr_b16 v[100:101], v159 offset:41984
	ds_read_b64_tr_b16 v[102:103], v159 offset:42496
	s_waitcnt lgkmcnt(0)
	v_mfma_f32_32x32x16_bf16 v[16:31], v[100:103], v[96:99], v[16:31]
	ds_read_b64_tr_b16 v[100:101], v159 offset:46080
	ds_read_b64_tr_b16 v[102:103], v159 offset:46592
	ds_read_b128 v[186:189], v164 offset:24576
	s_waitcnt lgkmcnt(1)
	v_mfma_f32_32x32x16_bf16 v[0:15], v[100:103], v[96:99], v[0:15]
	ds_read_b128 v[168:171], v161 offset:24576
	s_waitcnt lgkmcnt(0)
	v_mfma_f32_32x32x16_bf16 v[96:111], v[168:171], v[112:115], v[80:95]
	ds_read_b128 v[168:171], v162 offset:24576
	s_waitcnt lgkmcnt(0)
	v_mfma_f32_32x32x16_bf16 v[96:111], v[168:171], v[116:119], v[96:111]
	ds_read_b128 v[168:171], v163 offset:24576
	s_waitcnt lgkmcnt(0)
	v_mfma_f32_32x32x16_bf16 v[96:111], v[168:171], v[120:123], v[96:111]
	v_mfma_f32_32x32x16_bf16 v[96:111], v[186:189], v[124:127], v[96:111]
	s_nop 11
	v_maximum3_f32 v79, v96, v97, v97
	v_maximum3_f32 v79, v79, v98, v99
	v_maximum3_f32 v79, v79, v100, v101
	v_maximum3_f32 v79, v79, v102, v103
	v_maximum3_f32 v79, v79, v104, v105
	v_maximum3_f32 v79, v79, v106, v107
	v_maximum3_f32 v79, v79, v108, v109
	v_maximum3_f32 v79, v79, v110, v111
	v_mov_b32_e32 v166, v79
	s_nop 1
	v_permlane32_swap_b32_e32 v79, v166
	v_maximum3_f32 v79, v79, v166, v166
	v_cmp_lt_f32_e32 vcc, s80, v79
	s_cbranch_vccz .LBB0_369
	v_max_f32_e32 v64, v79, v79
	v_max_f32_e32 v64, 0, v64
	v_exp_f32_e64 v82, -v64
	v_add_f32_e32 v165, v165, v64
	v_xor_b32_e32 v80, 0x80000000, v165
	v_pk_add_f32 v[96:97], v[96:97], v[64:65] op_sel_hi:[1,0] neg_lo:[0,1] neg_hi:[0,1]
	v_mul_f32_e32 v78, v78, v82
	v_pk_add_f32 v[98:99], v[98:99], v[64:65] op_sel_hi:[1,0] neg_lo:[0,1] neg_hi:[0,1]
	v_pk_add_f32 v[100:101], v[100:101], v[64:65] op_sel_hi:[1,0] neg_lo:[0,1] neg_hi:[0,1]
	v_pk_add_f32 v[102:103], v[102:103], v[64:65] op_sel_hi:[1,0] neg_lo:[0,1] neg_hi:[0,1]
	v_pk_add_f32 v[104:105], v[104:105], v[64:65] op_sel_hi:[1,0] neg_lo:[0,1] neg_hi:[0,1]
	v_pk_add_f32 v[106:107], v[106:107], v[64:65] op_sel_hi:[1,0] neg_lo:[0,1] neg_hi:[0,1]
	v_pk_add_f32 v[108:109], v[108:109], v[64:65] op_sel_hi:[1,0] neg_lo:[0,1] neg_hi:[0,1]
	v_pk_add_f32 v[110:111], v[110:111], v[64:65] op_sel_hi:[1,0] neg_lo:[0,1] neg_hi:[0,1]
	v_pk_mul_f32 v[62:63], v[62:63], v[82:83] op_sel_hi:[1,0]
	v_pk_mul_f32 v[60:61], v[60:61], v[82:83] op_sel_hi:[1,0]
	v_pk_mul_f32 v[58:59], v[58:59], v[82:83] op_sel_hi:[1,0]
	v_pk_mul_f32 v[56:57], v[56:57], v[82:83] op_sel_hi:[1,0]
	v_pk_mul_f32 v[54:55], v[54:55], v[82:83] op_sel_hi:[1,0]
	v_pk_mul_f32 v[52:53], v[52:53], v[82:83] op_sel_hi:[1,0]
	v_pk_mul_f32 v[50:51], v[50:51], v[82:83] op_sel_hi:[1,0]
	v_pk_mul_f32 v[48:49], v[48:49], v[82:83] op_sel_hi:[1,0]
	v_pk_mul_f32 v[46:47], v[46:47], v[82:83] op_sel_hi:[1,0]
	v_pk_mul_f32 v[44:45], v[44:45], v[82:83] op_sel_hi:[1,0]
	v_pk_mul_f32 v[42:43], v[42:43], v[82:83] op_sel_hi:[1,0]
	v_pk_mul_f32 v[40:41], v[40:41], v[82:83] op_sel_hi:[1,0]
	v_pk_mul_f32 v[38:39], v[38:39], v[82:83] op_sel_hi:[1,0]
	v_pk_mul_f32 v[36:37], v[36:37], v[82:83] op_sel_hi:[1,0]
	v_pk_mul_f32 v[34:35], v[34:35], v[82:83] op_sel_hi:[1,0]
	v_pk_mul_f32 v[32:33], v[32:33], v[82:83] op_sel_hi:[1,0]
	v_pk_mul_f32 v[30:31], v[30:31], v[82:83] op_sel_hi:[1,0]
	v_pk_mul_f32 v[28:29], v[28:29], v[82:83] op_sel_hi:[1,0]
	v_pk_mul_f32 v[26:27], v[26:27], v[82:83] op_sel_hi:[1,0]
	v_pk_mul_f32 v[24:25], v[24:25], v[82:83] op_sel_hi:[1,0]
	v_pk_mul_f32 v[22:23], v[22:23], v[82:83] op_sel_hi:[1,0]
	v_pk_mul_f32 v[20:21], v[20:21], v[82:83] op_sel_hi:[1,0]
	v_pk_mul_f32 v[18:19], v[18:19], v[82:83] op_sel_hi:[1,0]
	v_pk_mul_f32 v[16:17], v[16:17], v[82:83] op_sel_hi:[1,0]
	v_pk_mul_f32 v[14:15], v[14:15], v[82:83] op_sel_hi:[1,0]
	v_pk_mul_f32 v[12:13], v[12:13], v[82:83] op_sel_hi:[1,0]
	v_pk_mul_f32 v[10:11], v[10:11], v[82:83] op_sel_hi:[1,0]
	v_pk_mul_f32 v[8:9], v[8:9], v[82:83] op_sel_hi:[1,0]
	v_pk_mul_f32 v[6:7], v[6:7], v[82:83] op_sel_hi:[1,0]
	v_pk_mul_f32 v[4:5], v[4:5], v[82:83] op_sel_hi:[1,0]
	v_pk_mul_f32 v[2:3], v[2:3], v[82:83] op_sel_hi:[1,0]
	v_pk_mul_f32 v[0:1], v[0:1], v[82:83] op_sel_hi:[1,0]
	v_mov_b32_e32 v81, v80
	v_mov_b32_e32 v82, v80
	v_mov_b32_e32 v83, v80
	v_mov_b32_e32 v84, v80
	v_mov_b32_e32 v85, v80
	v_mov_b32_e32 v86, v80
	v_mov_b32_e32 v87, v80
	v_mov_b32_e32 v88, v80
	v_mov_b32_e32 v89, v80
	v_mov_b32_e32 v90, v80
	v_mov_b32_e32 v91, v80
	v_mov_b32_e32 v92, v80
	v_mov_b32_e32 v93, v80
	v_mov_b32_e32 v94, v80
	v_mov_b32_e32 v95, v80
	s_branch .LBB0_370

; #define MFMA(a, b, c) __builtin_amdgcn_mfma_f32_32x32x16_bf16((a), (b), (c), 0, 0, 0)
; DI s16x4 vtr(const char* p) { return __builtin_bit_cast(s16x4, __builtin_amdgcn_ds_read_tr16_b64_v4i16((__attribute__((address_space(3))) v4i16_t*)(lds_cptr)p)); }
; DI bf16x8 cat8(s16x4 lo, s16x4 hi) { return __builtin_shufflevector(lo, hi, 0, 1, 2, 3, 4, 5, 6, 7); }
; DI float fexp2(float x) { return __builtin_amdgcn_exp2f(x); }
; template <int DV>
; DI void attn_core(const u16* __restrict__ P, size_t tokbase, int kcol, int vcol, int n1, int n2, int xs0,
;                   bool win, int tq, float m0, float l0, f32x16 (&o)[DV / 32], float& lsum, char* lds) {
;     ...
;       float la = 0.f;
; #pragma unroll
;       for (int reg = 0; reg < 16; ++reg) { const float e = fexp2(pt[reg]); pt[reg] = e; la += e; }
;       l += la;
; #pragma unroll
;       for (int s2 = 0; s2 < 2; ++s2) {
;         const bf16x8 pb = pack8(pt, s2);
;         const int s16 = 2 * ks + s2;
; #pragma unroll
;         for (int b = 0; b < DV / 32; ++b) {
;           const char* va = base + KB + b * 4096 + s16 * 1024 + trofs;
;           const bf16x8 vf = cat8(vtr(va), vtr(va + 512));
;           o[b] = MFMA(vf, pb, o[b]);
;         }
;       }
;     }
;     ...
;       if (it + 2 < ntiles) A_LOAD(kA, vA, it + 2);
;       compute(lds + STAGE, it + 1);
;       if (it + 2 < ntiles) A_STORE(kA, vA, 0);
;       __syncthreads();
;     }
.LBB0_369:
.LBB0_370:
	v_exp_f32_e32 v64, v96
	v_exp_f32_e32 v79, v97
	v_exp_f32_e32 v96, v98
	v_exp_f32_e32 v97, v99
	v_exp_f32_e32 v98, v100
	v_exp_f32_e32 v99, v101
	v_exp_f32_e32 v100, v102
	v_exp_f32_e32 v101, v103
	ds_read_b64_tr_b16 v[170:171], v159 offset:34816
	ds_read_b64_tr_b16 v[172:173], v159 offset:35328
	v_cvt_pk_bf16_f32 v166, v64, v79
	v_cvt_pk_bf16_f32 v167, v96, v97
	v_cvt_pk_bf16_f32 v168, v98, v99
	v_cvt_pk_bf16_f32 v169, v100, v101
	v_exp_f32_e32 v102, v104
	v_exp_f32_e32 v103, v105
	s_waitcnt lgkmcnt(0)
	v_mfma_f32_32x32x16_bf16 v[48:63], v[170:173], v[166:169], v[48:63]
	ds_read_b64_tr_b16 v[170:171], v159 offset:38912
	ds_read_b64_tr_b16 v[172:173], v159 offset:39424
	v_exp_f32_e32 v104, v106
	v_exp_f32_e32 v105, v107
	v_exp_f32_e32 v106, v108
	v_exp_f32_e32 v107, v109
	v_exp_f32_e32 v108, v110
	v_exp_f32_e32 v109, v111
	s_waitcnt lgkmcnt(0)
	v_mfma_f32_32x32x16_bf16 v[32:47], v[170:173], v[166:169], v[32:47]
	ds_read_b64_tr_b16 v[170:171], v159 offset:43008
	ds_read_b64_tr_b16 v[172:173], v159 offset:43520
	s_andn2_b64 vcc, exec, s[36:37]
	s_waitcnt lgkmcnt(0)
	v_mfma_f32_32x32x16_bf16 v[16:31], v[170:173], v[166:169], v[16:31]
	ds_read_b64_tr_b16 v[170:171], v159 offset:47104
	ds_read_b64_tr_b16 v[172:173], v159 offset:47616
	s_waitcnt lgkmcnt(0)
	v_mfma_f32_32x32x16_bf16 v[0:15], v[170:173], v[166:169], v[0:15]
	ds_read_b64_tr_b16 v[170:171], v159 offset:35840
	ds_read_b64_tr_b16 v[172:173], v159 offset:36352
	v_cvt_pk_bf16_f32 v166, v102, v103
	v_cvt_pk_bf16_f32 v167, v104, v105
	v_cvt_pk_bf16_f32 v168, v106, v107
	v_cvt_pk_bf16_f32 v169, v108, v109
	s_waitcnt lgkmcnt(0)
	s_nop 0
	v_mfma_f32_32x32x16_bf16 v[48:63], v[170:173], v[166:169], v[48:63]
	ds_read_b64_tr_b16 v[170:171], v159 offset:39936
	ds_read_b64_tr_b16 v[172:173], v159 offset:40448
	s_waitcnt lgkmcnt(0)
	v_mfma_f32_32x32x16_bf16 v[32:47], v[170:173], v[166:169], v[32:47]
	ds_read_b64_tr_b16 v[170:171], v159 offset:44032
	ds_read_b64_tr_b16 v[172:173], v159 offset:44544
	s_waitcnt lgkmcnt(0)
	v_mfma_f32_32x32x16_bf16 v[16:31], v[170:173], v[166:169], v[16:31]
	ds_read_b64_tr_b16 v[170:171], v159 offset:48128
	ds_read_b64_tr_b16 v[172:173], v159 offset:48640
	s_waitcnt lgkmcnt(0)
	v_mfma_f32_32x32x16_bf16 v[0:15], v[170:173], v[166:169], v[0:15]
	s_cbranch_vccnz .LBB0_351
	s_waitcnt vmcnt(5)
	ds_write_b128 v158, v[66:69]
	s_waitcnt vmcnt(4)
	ds_write_b128 v160, v[70:73]
	s_waitcnt vmcnt(3)
	ds_write_b128 v185, v[74:77] offset:8192
	s_waitcnt vmcnt(2)
	ds_write_b128 v185, v[128:131] offset:9216
	s_waitcnt vmcnt(1)
	ds_write_b128 v185, v[132:135] offset:10240
	s_waitcnt vmcnt(0)
	ds_write_b128 v185, v[136:139] offset:11264
	s_branch .LBB0_351

; #define MFMA(a, b, c) __builtin_amdgcn_mfma_f32_32x32x16_bf16((a), (b), (c), 0, 0, 0)
; DI int crow(int reg, int h) { return (reg & 3) + 8 * (reg >> 2) + 4 * h; }
; DI s16x4 vtr(const char* p) { return __builtin_bit_cast(s16x4, __builtin_amdgcn_ds_read_tr16_b64_v4i16((__attribute__((address_space(3))) v4i16_t*)(lds_cptr)p)); }
; template <int DV>
; DI void attn_core(const u16* __restrict__ P, size_t tokbase, int kcol, int vcol, int n1, int n2, int xs0,
;                   bool win, int tq, float m0, float l0, f32x16 (&o)[DV / 32], float& lsum, char* lds) {
;     ...
;     for (int ks = 0; ks < 2; ++ks) {
;       f32x16 pt = negm;
; #pragma unroll
;       for (int s = 0; s < 4; ++s) {
;         const int ch = 2 * s + h, key = 32 * ks + r;
;         const bf16x8 kf = *(const bf16x8*)(base + ch * 1024 + ((key ^ ch) * 16));
;         const bf16x8 qf = qreg[s];
;         pt = MFMA(kf, qf, pt);
;       }
;       if (domask) {
; #pragma unroll
;         for (int reg = 0; reg < 16; ++reg) {
;           const int d = tq - (kt0 + 32 * ks + crow(reg, h));
;           if (d > 128 || d < -128) pt[reg] = -1e30f;
;         }
;       }
;       float mloc = mx2(pt[0], pt[1]);
; #pragma unroll
;       for (int reg = 2; reg < 16; reg += 2) mloc = mx2(mx2(mloc, pt[reg]), pt[reg + 1]);
;       mloc = hmax(mloc);
;       const bool first = autoinit && it == 0 && ks == 0;
;       if (first || __builtin_amdgcn_ballot_w64(mloc > THR) != 0) {
;         const float d = first ? mloc : fmaxf(mloc, 0.f);
;         const float alpha = fexp2(-d);
;         m += d; l *= alpha;
; #pragma unroll
;         for (int reg = 0; reg < 16; ++reg) { negm[reg] = -m; pt[reg] -= d; }
; #pragma unroll
;         for (int b = 0; b < DV / 32; ++b)
; #pragma unroll
;           for (int reg = 0; reg < 16; ++reg) o[b][reg] *= alpha;
;       }
;       float la = 0.f;
; #pragma unroll
;       for (int reg = 0; reg < 16; ++reg) { const float e = fexp2(pt[reg]); pt[reg] = e; la += e; }
;       l += la;
; #pragma unroll
;       for (int s2 = 0; s2 < 2; ++s2) {
;         const bf16x8 pb = pack8(pt, s2);
;         const int s16 = 2 * ks + s2;
; #pragma unroll
;         for (int b = 0; b < DV / 32; ++b) {
;           const char* va = base + KB + b * 4096 + s16 * 1024 + trofs;
;           const bf16x8 vf = cat8(vtr(va), vtr(va + 512));
;           o[b] = MFMA(vf, pb, o[b]);
;         }
;       }
.LBB0_381:
.LBB0_382:
	v_exp_f32_e32 v82, v82
	v_exp_f32_e32 v83, v83
	v_exp_f32_e32 v84, v84
	v_exp_f32_e32 v85, v85
	v_add_f32_e32 v187, 0, v82
	v_exp_f32_e32 v86, v86
	v_add_f32_e32 v187, v83, v187
	v_exp_f32_e32 v87, v87
	v_add_f32_e32 v187, v84, v187
	v_exp_f32_e32 v88, v88
	v_add_f32_e32 v187, v85, v187
	v_exp_f32_e32 v89, v89
	v_add_f32_e32 v187, v86, v187
	v_add_f32_e32 v187, v87, v187
	v_add_f32_e32 v187, v88, v187
	v_add_f32_e32 v187, v89, v187
	v_cvt_pk_bf16_f32 v82, v82, v83
	v_cvt_pk_bf16_f32 v83, v84, v85
	v_cvt_pk_bf16_f32 v84, v86, v87
	v_cvt_pk_bf16_f32 v85, v88, v89
	ds_read_b64_tr_b16 v[86:87], v157 offset:8192
	ds_read_b64_tr_b16 v[88:89], v157 offset:8704
	s_waitcnt lgkmcnt(0)
	v_mfma_f32_32x32x16_bf16 v[48:63], v[86:89], v[82:85], v[48:63]
	ds_read_b64_tr_b16 v[86:87], v157 offset:12288
	ds_read_b64_tr_b16 v[88:89], v157 offset:12800
	v_exp_f32_e32 v90, v90
	v_exp_f32_e32 v91, v91
	v_exp_f32_e32 v92, v92
	v_exp_f32_e32 v93, v93
	v_exp_f32_e32 v94, v94
	v_exp_f32_e32 v95, v95
	s_waitcnt lgkmcnt(0)
	v_mfma_f32_32x32x16_bf16 v[32:47], v[86:89], v[82:85], v[32:47]
	ds_read_b64_tr_b16 v[86:87], v157 offset:16384
	ds_read_b64_tr_b16 v[88:89], v157 offset:16896
	v_exp_f32_e32 v96, v96
	v_exp_f32_e32 v97, v97
	v_add_f32_e32 v187, v90, v187
	v_add_f32_e32 v187, v91, v187
	v_add_f32_e32 v187, v92, v187
	v_add_f32_e32 v187, v93, v187
	s_waitcnt lgkmcnt(0)
	v_mfma_f32_32x32x16_bf16 v[16:31], v[86:89], v[82:85], v[16:31]
	ds_read_b64_tr_b16 v[86:87], v157 offset:20480
	ds_read_b64_tr_b16 v[88:89], v157 offset:20992
	v_add_f32_e32 v187, v94, v187
	v_add_f32_e32 v187, v95, v187
	v_add_f32_e32 v187, v96, v187
	v_add_f32_e32 v187, v97, v187
	v_add_f32_e32 v187, v186, v187
	s_waitcnt lgkmcnt(0)
	v_mfma_f32_32x32x16_bf16 v[0:15], v[86:89], v[82:85], v[0:15]
	ds_read_b64_tr_b16 v[86:87], v157 offset:9216
	ds_read_b64_tr_b16 v[88:89], v157 offset:9728
	v_cvt_pk_bf16_f32 v82, v90, v91
	v_cvt_pk_bf16_f32 v83, v92, v93
	v_cvt_pk_bf16_f32 v84, v94, v95
	v_cvt_pk_bf16_f32 v85, v96, v97
	s_waitcnt lgkmcnt(0)
	s_nop 0
	v_mfma_f32_32x32x16_bf16 v[48:63], v[86:89], v[82:85], v[48:63]
	ds_read_b64_tr_b16 v[86:87], v157 offset:13312
	ds_read_b64_tr_b16 v[88:89], v157 offset:13824
	s_waitcnt lgkmcnt(0)
	v_mfma_f32_32x32x16_bf16 v[32:47], v[86:89], v[82:85], v[32:47]
	ds_read_b64_tr_b16 v[86:87], v157 offset:17408
	ds_read_b64_tr_b16 v[88:89], v157 offset:17920
	s_waitcnt lgkmcnt(0)
	v_mfma_f32_32x32x16_bf16 v[16:31], v[86:89], v[82:85], v[16:31]
	ds_read_b64_tr_b16 v[86:87], v157 offset:21504
	ds_read_b64_tr_b16 v[88:89], v157 offset:22016
	ds_read_b128 v[206:209], v162
	s_waitcnt lgkmcnt(1)
	v_mfma_f32_32x32x16_bf16 v[0:15], v[86:89], v[82:85], v[0:15]
	s_waitcnt lgkmcnt(0)
	v_mfma_f32_32x32x16_bf16 v[82:97], v[206:209], v[98:101], v[66:81]
	ds_read_b128 v[206:209], v163
	s_waitcnt lgkmcnt(0)
	v_mfma_f32_32x32x16_bf16 v[82:97], v[206:209], v[102:105], v[82:97]
	ds_read_b128 v[206:209], v164
	s_waitcnt lgkmcnt(0)
	v_mfma_f32_32x32x16_bf16 v[82:97], v[206:209], v[106:109], v[82:97]
	ds_read_b128 v[206:209], v165
	s_waitcnt lgkmcnt(0)
	v_mfma_f32_32x32x16_bf16 v[82:97], v[206:209], v[110:113], v[82:97]
	s_nop 11
	v_maximum3_f32 v186, v82, v83, v83
	v_maximum3_f32 v186, v186, v84, v85
	v_maximum3_f32 v186, v186, v86, v87
	v_maximum3_f32 v186, v186, v88, v89
	v_maximum3_f32 v186, v186, v90, v91
	v_maximum3_f32 v186, v186, v92, v93
	v_maximum3_f32 v186, v186, v94, v95
	v_maximum3_f32 v186, v186, v96, v97
	v_mov_b32_e32 v188, v186
	s_nop 1
	v_permlane32_swap_b32_e32 v186, v188
	v_maximum3_f32 v186, v186, v188, v188
	v_cmp_lt_f32_e32 vcc, s80, v186
	s_cbranch_vccz .LBB0_384
; DI float fexp2(float x) { return __builtin_amdgcn_exp2f(x); }
; template <int DV>
; DI void attn_core(const u16* __restrict__ P, size_t tokbase, int kcol, int vcol, int n1, int n2, int xs0,
;                   bool win, int tq, float m0, float l0, f32x16 (&o)[DV / 32], float& lsum, char* lds) {
;     ...
;       if (first || __builtin_amdgcn_ballot_w64(mloc > THR) != 0) {
;         const float d = first ? mloc : fmaxf(mloc, 0.f);
;         const float alpha = fexp2(-d);
;         m += d; l *= alpha;
; #pragma unroll
;         for (int reg = 0; reg < 16; ++reg) { negm[reg] = -m; pt[reg] -= d; }
; #pragma unroll
;         for (int b = 0; b < DV / 32; ++b)
; #pragma unroll
;           for (int reg = 0; reg < 16; ++reg) o[b][reg] *= alpha;
;       }
	v_max_f32_e32 v66, v186, v186
	v_max_f32_e32 v68, 0, v66
	v_exp_f32_e64 v70, -v68
	v_add_f32_e32 v166, v166, v68
	v_xor_b32_e32 v66, 0x80000000, v166
	v_pk_add_f32 v[82:83], v[82:83], v[68:69] op_sel_hi:[1,0] neg_lo:[0,1] neg_hi:[0,1]
	v_mul_f32_e32 v187, v187, v70
	v_pk_add_f32 v[84:85], v[84:85], v[68:69] op_sel_hi:[1,0] neg_lo:[0,1] neg_hi:[0,1]
	v_pk_add_f32 v[86:87], v[86:87], v[68:69] op_sel_hi:[1,0] neg_lo:[0,1] neg_hi:[0,1]
	v_pk_add_f32 v[88:89], v[88:89], v[68:69] op_sel_hi:[1,0] neg_lo:[0,1] neg_hi:[0,1]
	v_pk_add_f32 v[90:91], v[90:91], v[68:69] op_sel_hi:[1,0] neg_lo:[0,1] neg_hi:[0,1]
	v_pk_add_f32 v[92:93], v[92:93], v[68:69] op_sel_hi:[1,0] neg_lo:[0,1] neg_hi:[0,1]
	v_pk_add_f32 v[94:95], v[94:95], v[68:69] op_sel_hi:[1,0] neg_lo:[0,1] neg_hi:[0,1]
	v_pk_add_f32 v[96:97], v[96:97], v[68:69] op_sel_hi:[1,0] neg_lo:[0,1] neg_hi:[0,1]
	v_pk_mul_f32 v[62:63], v[62:63], v[70:71] op_sel_hi:[1,0]
	v_pk_mul_f32 v[60:61], v[60:61], v[70:71] op_sel_hi:[1,0]
	v_pk_mul_f32 v[58:59], v[58:59], v[70:71] op_sel_hi:[1,0]
	v_pk_mul_f32 v[56:57], v[56:57], v[70:71] op_sel_hi:[1,0]
	v_pk_mul_f32 v[54:55], v[54:55], v[70:71] op_sel_hi:[1,0]
	v_pk_mul_f32 v[52:53], v[52:53], v[70:71] op_sel_hi:[1,0]
	v_pk_mul_f32 v[50:51], v[50:51], v[70:71] op_sel_hi:[1,0]
	v_pk_mul_f32 v[48:49], v[48:49], v[70:71] op_sel_hi:[1,0]
	v_pk_mul_f32 v[46:47], v[46:47], v[70:71] op_sel_hi:[1,0]
	v_pk_mul_f32 v[44:45], v[44:45], v[70:71] op_sel_hi:[1,0]
	v_pk_mul_f32 v[42:43], v[42:43], v[70:71] op_sel_hi:[1,0]
	v_pk_mul_f32 v[40:41], v[40:41], v[70:71] op_sel_hi:[1,0]
	v_pk_mul_f32 v[38:39], v[38:39], v[70:71] op_sel_hi:[1,0]
	v_pk_mul_f32 v[36:37], v[36:37], v[70:71] op_sel_hi:[1,0]
	v_pk_mul_f32 v[34:35], v[34:35], v[70:71] op_sel_hi:[1,0]
	v_pk_mul_f32 v[32:33], v[32:33], v[70:71] op_sel_hi:[1,0]
	v_pk_mul_f32 v[30:31], v[30:31], v[70:71] op_sel_hi:[1,0]
	v_pk_mul_f32 v[28:29], v[28:29], v[70:71] op_sel_hi:[1,0]
	v_pk_mul_f32 v[26:27], v[26:27], v[70:71] op_sel_hi:[1,0]
	v_pk_mul_f32 v[24:25], v[24:25], v[70:71] op_sel_hi:[1,0]
	v_pk_mul_f32 v[22:23], v[22:23], v[70:71] op_sel_hi:[1,0]
	v_pk_mul_f32 v[20:21], v[20:21], v[70:71] op_sel_hi:[1,0]
	v_pk_mul_f32 v[18:19], v[18:19], v[70:71] op_sel_hi:[1,0]
	v_pk_mul_f32 v[16:17], v[16:17], v[70:71] op_sel_hi:[1,0]
	v_pk_mul_f32 v[14:15], v[14:15], v[70:71] op_sel_hi:[1,0]
	v_pk_mul_f32 v[12:13], v[12:13], v[70:71] op_sel_hi:[1,0]
	v_pk_mul_f32 v[10:11], v[10:11], v[70:71] op_sel_hi:[1,0]
	v_pk_mul_f32 v[8:9], v[8:9], v[70:71] op_sel_hi:[1,0]
	v_pk_mul_f32 v[6:7], v[6:7], v[70:71] op_sel_hi:[1,0]
	v_pk_mul_f32 v[4:5], v[4:5], v[70:71] op_sel_hi:[1,0]
	v_pk_mul_f32 v[2:3], v[2:3], v[70:71] op_sel_hi:[1,0]
	v_pk_mul_f32 v[0:1], v[0:1], v[70:71] op_sel_hi:[1,0]
	v_mov_b32_e32 v67, v66
	v_mov_b32_e32 v68, v66
	v_mov_b32_e32 v69, v66
	v_mov_b32_e32 v70, v66
	v_mov_b32_e32 v71, v66
	v_mov_b32_e32 v72, v66
	v_mov_b32_e32 v73, v66
	v_mov_b32_e32 v74, v66
	v_mov_b32_e32 v75, v66
	v_mov_b32_e32 v76, v66
	v_mov_b32_e32 v77, v66
	v_mov_b32_e32 v78, v66
	v_mov_b32_e32 v79, v66
	v_mov_b32_e32 v80, v66
	v_mov_b32_e32 v81, v66
	v_mov_b32_e32 v148, v66
	v_mov_b32_e32 v167, v66
	v_mov_b32_e32 v169, v66
	v_mov_b32_e32 v170, v66
	v_mov_b32_e32 v171, v66
	v_mov_b32_e32 v172, v66
	v_mov_b32_e32 v173, v66
	v_mov_b32_e32 v175, v66
	v_mov_b32_e32 v176, v66
	v_mov_b32_e32 v177, v66
	v_mov_b32_e32 v178, v66
	v_mov_b32_e32 v179, v66
	v_mov_b32_e32 v180, v66
	v_mov_b32_e32 v181, v66
	v_mov_b32_e32 v183, v66
	v_mov_b32_e32 v184, v66

; #define MFMA(a, b, c) __builtin_amdgcn_mfma_f32_32x32x16_bf16((a), (b), (c), 0, 0, 0)
; DI int crow(int reg, int h) { return (reg & 3) + 8 * (reg >> 2) + 4 * h; }
; DI s16x4 vtr(const char* p) { return __builtin_bit_cast(s16x4, __builtin_amdgcn_ds_read_tr16_b64_v4i16((__attribute__((address_space(3))) v4i16_t*)(lds_cptr)p)); }
; template <int DV>
; DI void attn_core(const u16* __restrict__ P, size_t tokbase, int kcol, int vcol, int n1, int n2, int xs0,
;                   bool win, int tq, float m0, float l0, f32x16 (&o)[DV / 32], float& lsum, char* lds) {
;     ...
;     for (int ks = 0; ks < 2; ++ks) {
;       f32x16 pt = negm;
; #pragma unroll
;       for (int s = 0; s < 4; ++s) {
;         const int ch = 2 * s + h, key = 32 * ks + r;
;         const bf16x8 kf = *(const bf16x8*)(base + ch * 1024 + ((key ^ ch) * 16));
;         const bf16x8 qf = qreg[s];
;         pt = MFMA(kf, qf, pt);
;       }
;       if (domask) {
; #pragma unroll
;         for (int reg = 0; reg < 16; ++reg) {
;           const int d = tq - (kt0 + 32 * ks + crow(reg, h));
;           if (d > 128 || d < -128) pt[reg] = -1e30f;
;         }
;       }
;       float mloc = mx2(pt[0], pt[1]);
; #pragma unroll
;       for (int reg = 2; reg < 16; reg += 2) mloc = mx2(mx2(mloc, pt[reg]), pt[reg + 1]);
;       mloc = hmax(mloc);
;       const bool first = autoinit && it == 0 && ks == 0;
;       if (first || __builtin_amdgcn_ballot_w64(mloc > THR) != 0) {
;         const float d = first ? mloc : fmaxf(mloc, 0.f);
;         const float alpha = fexp2(-d);
;         m += d; l *= alpha;
; #pragma unroll
;         for (int reg = 0; reg < 16; ++reg) { negm[reg] = -m; pt[reg] -= d; }
; #pragma unroll
;         for (int b = 0; b < DV / 32; ++b)
; #pragma unroll
;           for (int reg = 0; reg < 16; ++reg) o[b][reg] *= alpha;
;       }
;       float la = 0.f;
; #pragma unroll
;       for (int reg = 0; reg < 16; ++reg) { const float e = fexp2(pt[reg]); pt[reg] = e; la += e; }
;       l += la;
; #pragma unroll
;       for (int s2 = 0; s2 < 2; ++s2) {
;         const bf16x8 pb = pack8(pt, s2);
;         const int s16 = 2 * ks + s2;
; #pragma unroll
;         for (int b = 0; b < DV / 32; ++b) {
;           const char* va = base + KB + b * 4096 + s16 * 1024 + trofs;
;           const bf16x8 vf = cat8(vtr(va), vtr(va + 512));
;           o[b] = MFMA(vf, pb, o[b]);
;         }
;       }
.LBB0_388:
	v_exp_f32_e32 v82, v82
	v_exp_f32_e32 v83, v83
	v_exp_f32_e32 v84, v84
	v_exp_f32_e32 v85, v85
	v_add_f32_e32 v145, 0, v82
	v_exp_f32_e32 v86, v86
	v_add_f32_e32 v145, v83, v145
	v_exp_f32_e32 v87, v87
	v_add_f32_e32 v145, v84, v145
	v_exp_f32_e32 v88, v88
	v_add_f32_e32 v145, v85, v145
	v_exp_f32_e32 v89, v89
	v_add_f32_e32 v145, v86, v145
	v_add_f32_e32 v145, v87, v145
	v_add_f32_e32 v145, v88, v145
	v_add_f32_e32 v145, v89, v145
	v_cvt_pk_bf16_f32 v82, v82, v83
	v_cvt_pk_bf16_f32 v83, v84, v85
	v_cvt_pk_bf16_f32 v84, v86, v87
	v_cvt_pk_bf16_f32 v85, v88, v89
	ds_read_b64_tr_b16 v[86:87], v157 offset:32768
	ds_read_b64_tr_b16 v[88:89], v157 offset:33280
	s_waitcnt lgkmcnt(0)
	v_mfma_f32_32x32x16_bf16 v[48:63], v[86:89], v[82:85], v[48:63]
	ds_read_b64_tr_b16 v[86:87], v157 offset:36864
	ds_read_b64_tr_b16 v[88:89], v157 offset:37376
	v_exp_f32_e32 v90, v90
	v_exp_f32_e32 v91, v91
	v_exp_f32_e32 v92, v92
	v_exp_f32_e32 v93, v93
	v_exp_f32_e32 v94, v94
	v_exp_f32_e32 v95, v95
	s_waitcnt lgkmcnt(0)
	v_mfma_f32_32x32x16_bf16 v[32:47], v[86:89], v[82:85], v[32:47]
	ds_read_b64_tr_b16 v[86:87], v157 offset:40960
	ds_read_b64_tr_b16 v[88:89], v157 offset:41472
	v_exp_f32_e32 v96, v96
	v_exp_f32_e32 v97, v97
	v_add_f32_e32 v145, v90, v145
	v_add_f32_e32 v145, v91, v145
	v_add_f32_e32 v145, v92, v145
	v_add_f32_e32 v145, v93, v145
	s_waitcnt lgkmcnt(0)
	v_mfma_f32_32x32x16_bf16 v[16:31], v[86:89], v[82:85], v[16:31]
	ds_read_b64_tr_b16 v[86:87], v157 offset:45056
	ds_read_b64_tr_b16 v[88:89], v157 offset:45568
	v_add_f32_e32 v145, v94, v145
	v_add_f32_e32 v145, v95, v145
	v_add_f32_e32 v145, v96, v145
	v_add_f32_e32 v145, v97, v145
	v_add_f32_e32 v144, v144, v145
	s_waitcnt lgkmcnt(0)
	v_mfma_f32_32x32x16_bf16 v[0:15], v[86:89], v[82:85], v[0:15]
	ds_read_b64_tr_b16 v[86:87], v157 offset:33792
	ds_read_b64_tr_b16 v[88:89], v157 offset:34304
	v_cvt_pk_bf16_f32 v82, v90, v91
	v_cvt_pk_bf16_f32 v83, v92, v93
	v_cvt_pk_bf16_f32 v84, v94, v95
	v_cvt_pk_bf16_f32 v85, v96, v97
	s_waitcnt lgkmcnt(0)
	s_nop 0
	v_mfma_f32_32x32x16_bf16 v[48:63], v[86:89], v[82:85], v[48:63]
	ds_read_b64_tr_b16 v[86:87], v157 offset:37888
	ds_read_b64_tr_b16 v[88:89], v157 offset:38400
	s_waitcnt lgkmcnt(0)
	v_mfma_f32_32x32x16_bf16 v[32:47], v[86:89], v[82:85], v[32:47]
	ds_read_b64_tr_b16 v[86:87], v157 offset:41984
	ds_read_b64_tr_b16 v[88:89], v157 offset:42496
	s_waitcnt lgkmcnt(0)
	v_mfma_f32_32x32x16_bf16 v[16:31], v[86:89], v[82:85], v[16:31]
	ds_read_b64_tr_b16 v[86:87], v157 offset:46080
	ds_read_b64_tr_b16 v[88:89], v157 offset:46592
	ds_read_b128 v[206:209], v165 offset:24576
	s_waitcnt lgkmcnt(1)
	v_mfma_f32_32x32x16_bf16 v[0:15], v[86:89], v[82:85], v[0:15]
	ds_read_b128 v[170:173], v162 offset:24576
	s_waitcnt lgkmcnt(0)
	v_mfma_f32_32x32x16_bf16 v[82:97], v[170:173], v[98:101], v[66:81]
	ds_read_b128 v[170:173], v163 offset:24576
	s_waitcnt lgkmcnt(0)
	v_mfma_f32_32x32x16_bf16 v[82:97], v[170:173], v[102:105], v[82:97]
	ds_read_b128 v[170:173], v164 offset:24576
	s_waitcnt lgkmcnt(0)
	v_mfma_f32_32x32x16_bf16 v[82:97], v[170:173], v[106:109], v[82:97]
	v_mfma_f32_32x32x16_bf16 v[82:97], v[206:209], v[110:113], v[82:97]
	s_nop 11
	v_maximum3_f32 v148, v82, v83, v83
	v_maximum3_f32 v148, v148, v84, v85
	v_maximum3_f32 v148, v148, v86, v87
	v_maximum3_f32 v148, v148, v88, v89
	v_maximum3_f32 v148, v148, v90, v91
	v_maximum3_f32 v148, v148, v92, v93
	v_maximum3_f32 v148, v148, v94, v95
	v_maximum3_f32 v148, v148, v96, v97
	v_mov_b32_e32 v167, v148
	s_nop 1
	v_permlane32_swap_b32_e32 v148, v167
	v_maximum3_f32 v148, v148, v167, v167
	v_cmp_lt_f32_e32 vcc, s80, v148
	s_cbranch_vccz .LBB0_391
	v_max_f32_e32 v148, v148, v148
	v_max_f32_e32 v68, 0, v148
	v_exp_f32_e64 v70, -v68
	v_add_f32_e32 v166, v166, v68
	v_xor_b32_e32 v66, 0x80000000, v166
	v_pk_add_f32 v[82:83], v[82:83], v[68:69] op_sel_hi:[1,0] neg_lo:[0,1] neg_hi:[0,1]
	v_mul_f32_e32 v144, v144, v70
	v_pk_add_f32 v[84:85], v[84:85], v[68:69] op_sel_hi:[1,0] neg_lo:[0,1] neg_hi:[0,1]
	v_pk_add_f32 v[86:87], v[86:87], v[68:69] op_sel_hi:[1,0] neg_lo:[0,1] neg_hi:[0,1]
	v_pk_add_f32 v[88:89], v[88:89], v[68:69] op_sel_hi:[1,0] neg_lo:[0,1] neg_hi:[0,1]
	v_pk_add_f32 v[90:91], v[90:91], v[68:69] op_sel_hi:[1,0] neg_lo:[0,1] neg_hi:[0,1]
	v_pk_add_f32 v[92:93], v[92:93], v[68:69] op_sel_hi:[1,0] neg_lo:[0,1] neg_hi:[0,1]
	v_pk_add_f32 v[94:95], v[94:95], v[68:69] op_sel_hi:[1,0] neg_lo:[0,1] neg_hi:[0,1]
	v_pk_add_f32 v[96:97], v[96:97], v[68:69] op_sel_hi:[1,0] neg_lo:[0,1] neg_hi:[0,1]
	v_pk_mul_f32 v[62:63], v[62:63], v[70:71] op_sel_hi:[1,0]
	v_pk_mul_f32 v[60:61], v[60:61], v[70:71] op_sel_hi:[1,0]
	v_pk_mul_f32 v[58:59], v[58:59], v[70:71] op_sel_hi:[1,0]
	v_pk_mul_f32 v[56:57], v[56:57], v[70:71] op_sel_hi:[1,0]
	v_pk_mul_f32 v[54:55], v[54:55], v[70:71] op_sel_hi:[1,0]
	v_pk_mul_f32 v[52:53], v[52:53], v[70:71] op_sel_hi:[1,0]
	v_pk_mul_f32 v[50:51], v[50:51], v[70:71] op_sel_hi:[1,0]
	v_pk_mul_f32 v[48:49], v[48:49], v[70:71] op_sel_hi:[1,0]
	v_pk_mul_f32 v[46:47], v[46:47], v[70:71] op_sel_hi:[1,0]
	v_pk_mul_f32 v[44:45], v[44:45], v[70:71] op_sel_hi:[1,0]
	v_pk_mul_f32 v[42:43], v[42:43], v[70:71] op_sel_hi:[1,0]
	v_pk_mul_f32 v[40:41], v[40:41], v[70:71] op_sel_hi:[1,0]
	v_pk_mul_f32 v[38:39], v[38:39], v[70:71] op_sel_hi:[1,0]
	v_pk_mul_f32 v[36:37], v[36:37], v[70:71] op_sel_hi:[1,0]
	v_pk_mul_f32 v[34:35], v[34:35], v[70:71] op_sel_hi:[1,0]
	v_pk_mul_f32 v[32:33], v[32:33], v[70:71] op_sel_hi:[1,0]
	v_pk_mul_f32 v[30:31], v[30:31], v[70:71] op_sel_hi:[1,0]
	v_pk_mul_f32 v[28:29], v[28:29], v[70:71] op_sel_hi:[1,0]
	v_pk_mul_f32 v[26:27], v[26:27], v[70:71] op_sel_hi:[1,0]
	v_pk_mul_f32 v[24:25], v[24:25], v[70:71] op_sel_hi:[1,0]
	v_pk_mul_f32 v[22:23], v[22:23], v[70:71] op_sel_hi:[1,0]
	v_pk_mul_f32 v[20:21], v[20:21], v[70:71] op_sel_hi:[1,0]
	v_pk_mul_f32 v[18:19], v[18:19], v[70:71] op_sel_hi:[1,0]
	v_pk_mul_f32 v[16:17], v[16:17], v[70:71] op_sel_hi:[1,0]
	v_pk_mul_f32 v[14:15], v[14:15], v[70:71] op_sel_hi:[1,0]
	v_pk_mul_f32 v[12:13], v[12:13], v[70:71] op_sel_hi:[1,0]
	v_pk_mul_f32 v[10:11], v[10:11], v[70:71] op_sel_hi:[1,0]
	v_pk_mul_f32 v[8:9], v[8:9], v[70:71] op_sel_hi:[1,0]
	v_pk_mul_f32 v[6:7], v[6:7], v[70:71] op_sel_hi:[1,0]
	v_pk_mul_f32 v[4:5], v[4:5], v[70:71] op_sel_hi:[1,0]
	v_pk_mul_f32 v[2:3], v[2:3], v[70:71] op_sel_hi:[1,0]
	v_pk_mul_f32 v[0:1], v[0:1], v[70:71] op_sel_hi:[1,0]
	v_mov_b32_e32 v67, v66
	v_mov_b32_e32 v68, v66
	v_mov_b32_e32 v69, v66
	v_mov_b32_e32 v70, v66
	v_mov_b32_e32 v71, v66
	v_mov_b32_e32 v72, v66
	v_mov_b32_e32 v73, v66
	v_mov_b32_e32 v74, v66
	v_mov_b32_e32 v75, v66
	v_mov_b32_e32 v76, v66
	v_mov_b32_e32 v77, v66
	v_mov_b32_e32 v78, v66
	v_mov_b32_e32 v79, v66
	v_mov_b32_e32 v80, v66
	v_mov_b32_e32 v81, v66
	s_branch .LBB0_392

; #define MFMA(a, b, c) __builtin_amdgcn_mfma_f32_32x32x16_bf16((a), (b), (c), 0, 0, 0)
; DI s16x4 vtr(const char* p) { return __builtin_bit_cast(s16x4, __builtin_amdgcn_ds_read_tr16_b64_v4i16((__attribute__((address_space(3))) v4i16_t*)(lds_cptr)p)); }
; DI bf16x8 cat8(s16x4 lo, s16x4 hi) { return __builtin_shufflevector(lo, hi, 0, 1, 2, 3, 4, 5, 6, 7); }
; DI float fexp2(float x) { return __builtin_amdgcn_exp2f(x); }
; template <int DV>
; DI void attn_core(const u16* __restrict__ P, size_t tokbase, int kcol, int vcol, int n1, int n2, int xs0,
;                   bool win, int tq, float m0, float l0, f32x16 (&o)[DV / 32], float& lsum, char* lds) {
;     ...
;       float la = 0.f;
; #pragma unroll
;       for (int reg = 0; reg < 16; ++reg) { const float e = fexp2(pt[reg]); pt[reg] = e; la += e; }
;       l += la;
; #pragma unroll
;       for (int s2 = 0; s2 < 2; ++s2) {
;         const bf16x8 pb = pack8(pt, s2);
;         const int s16 = 2 * ks + s2;
; #pragma unroll
;         for (int b = 0; b < DV / 32; ++b) {
;           const char* va = base + KB + b * 4096 + s16 * 1024 + trofs;
;           const bf16x8 vf = cat8(vtr(va), vtr(va + 512));
;           o[b] = MFMA(vf, pb, o[b]);
;         }
;       }
;     ...
;       if (it + 2 < ntiles) A_STORE(kA, vA, 0);
;       __syncthreads();
.LBB0_391:
.LBB0_392:
	v_exp_f32_e32 v82, v82
	v_exp_f32_e32 v83, v83
	v_exp_f32_e32 v84, v84
	v_exp_f32_e32 v85, v85
	v_exp_f32_e32 v86, v86
	v_exp_f32_e32 v87, v87
	v_exp_f32_e32 v88, v88
	v_exp_f32_e32 v89, v89
	ds_read_b64_tr_b16 v[172:173], v157 offset:34816
	ds_read_b64_tr_b16 v[174:175], v157 offset:35328
	v_cvt_pk_bf16_f32 v168, v82, v83
	v_cvt_pk_bf16_f32 v169, v84, v85
	v_cvt_pk_bf16_f32 v170, v86, v87
	v_cvt_pk_bf16_f32 v171, v88, v89
	v_exp_f32_e32 v90, v90
	v_exp_f32_e32 v91, v91
	s_waitcnt lgkmcnt(0)
	v_mfma_f32_32x32x16_bf16 v[48:63], v[172:175], v[168:171], v[48:63]
	ds_read_b64_tr_b16 v[172:173], v157 offset:38912
	ds_read_b64_tr_b16 v[174:175], v157 offset:39424
	v_exp_f32_e32 v92, v92
	v_exp_f32_e32 v93, v93
	v_exp_f32_e32 v94, v94
	v_exp_f32_e32 v95, v95
	v_exp_f32_e32 v96, v96
	v_exp_f32_e32 v97, v97
	s_waitcnt lgkmcnt(0)
	v_mfma_f32_32x32x16_bf16 v[32:47], v[172:175], v[168:171], v[32:47]
	ds_read_b64_tr_b16 v[172:173], v157 offset:43008
	ds_read_b64_tr_b16 v[174:175], v157 offset:43520
	s_andn2_b64 vcc, exec, s[30:31]
	s_waitcnt lgkmcnt(0)
	v_mfma_f32_32x32x16_bf16 v[16:31], v[172:175], v[168:171], v[16:31]
	ds_read_b64_tr_b16 v[172:173], v157 offset:47104
	ds_read_b64_tr_b16 v[174:175], v157 offset:47616
	s_waitcnt lgkmcnt(0)
	v_mfma_f32_32x32x16_bf16 v[0:15], v[172:175], v[168:171], v[0:15]
	ds_read_b64_tr_b16 v[172:173], v157 offset:35840
	ds_read_b64_tr_b16 v[174:175], v157 offset:36352
	v_cvt_pk_bf16_f32 v168, v90, v91
	v_cvt_pk_bf16_f32 v169, v92, v93
	v_cvt_pk_bf16_f32 v170, v94, v95
	v_cvt_pk_bf16_f32 v171, v96, v97
	s_waitcnt lgkmcnt(0)
	s_nop 0
	v_mfma_f32_32x32x16_bf16 v[48:63], v[172:175], v[168:171], v[48:63]
	ds_read_b64_tr_b16 v[172:173], v157 offset:39936
	ds_read_b64_tr_b16 v[174:175], v157 offset:40448
	s_waitcnt lgkmcnt(0)
	v_mfma_f32_32x32x16_bf16 v[32:47], v[172:175], v[168:171], v[32:47]
	ds_read_b64_tr_b16 v[172:173], v157 offset:44032
	ds_read_b64_tr_b16 v[174:175], v157 offset:44544
	s_waitcnt lgkmcnt(0)
	v_mfma_f32_32x32x16_bf16 v[16:31], v[172:175], v[168:171], v[16:31]
	ds_read_b64_tr_b16 v[172:173], v157 offset:48128
	ds_read_b64_tr_b16 v[174:175], v157 offset:48640
	s_waitcnt lgkmcnt(0)
	v_mfma_f32_32x32x16_bf16 v[0:15], v[172:175], v[168:171], v[0:15]
	s_cbranch_vccnz .LBB0_373
	s_waitcnt vmcnt(5)
	ds_write_b128 v153, v[114:117]
	s_waitcnt vmcnt(4)
	ds_write_b128 v154, v[118:121]
	s_waitcnt vmcnt(3)
	ds_write_b128 v186, v[122:125] offset:8192
	s_waitcnt vmcnt(2)
	ds_write_b128 v186, v[126:129] offset:9216
	s_waitcnt vmcnt(1)
	ds_write_b128 v186, v[130:133] offset:10240
	s_waitcnt vmcnt(0)
	ds_write_b128 v186, v[134:137] offset:11264
	s_branch .LBB0_373
